# LRU output stores: scalar base + 32-bit lane offset (two 64-bit VALU adds per iteration removed)
# baseline (speedup 1.0000x reference)
.LBB0_364:
	s_lshl_b32 s76, s80, 6
	s_addk_i32 s76, 0xff00
	s_mov_b32 s77, s69
	s_add_u32 s78, s94, s36
	s_addc_u32 s79, s95, s37
	s_lshl_b64 s[36:37], s[76:77], 11
	s_add_u32 s36, s78, s36
	s_addc_u32 s37, s79, s37
	v_cvt_pk_bf16_f32 v11, v12, v13
	s_waitcnt lgkmcnt(0)
	v_lshlrev_b32_e32 v0, 1, v116
	global_store_dwordx4 v0, v[8:11], s[36:37]

.LBB0_410:
	s_add_u32 s76, s94, s36
	s_addc_u32 s77, s95, s37
	s_lshl_b64 s[36:37], s[68:69], 11
	s_add_u32 s36, s76, s36
	s_addc_u32 s37, s77, s37
	v_cvt_pk_bf16_f32 v11, v12, v13
	s_waitcnt lgkmcnt(0)
	v_lshlrev_b32_e32 v0, 1, v116
	global_store_dwordx4 v0, v[8:11], s[36:37]
